# P2 q/kv epilogues: the xor-16 / xor-32 row-sum shuffles done with v_permlane16/32_swap instead of ds_bpermute round trips
# baseline (speedup 1.0000x reference)
.LBB0_396:
	s_cmp_lg_u32 s54, 2
	s_cselect_b64 s[2:3], -1, 0
	s_lshl_b32 s56, s54, 8
	s_ashr_i32 s57, s56, 31
	v_readlane_b32 s16, v253, 5
	s_lshl_b64 s[8:9], s[56:57], 2
	v_readlane_b32 s20, v253, 9
	v_readlane_b32 s17, v253, 6
	v_readlane_b32 s21, v253, 10
	s_add_u32 s11, s20, s8
	s_addc_u32 s17, s21, s9
	s_cmp_eq_u32 s54, 2
	s_cselect_b64 s[94:95], -1, 0
	s_and_b64 s[8:9], s[94:95], exec
	v_readlane_b32 s8, v252, 6
	s_cselect_b32 s9, s8, s17
	v_readlane_b32 s8, v252, 5
	s_cselect_b32 s8, s8, s11
	s_nop 3
	global_load_dwordx4 v[128:131], v162, s[8:9] offset:16
	global_load_dwordx4 v[132:135], v162, s[8:9]
	v_and_b32_e32 v163, 64, v182
	v_xor_b32_e32 v144, 16, v182
	v_add_u32_e32 v163, 64, v163
	v_cmp_lt_i32_e32 vcc, v144, v163
	v_mul_f32_e32 v164, v127, v127
	v_fmac_f32_e32 v164, v126, v126
	v_cndmask_b32_e32 v144, v182, v144, vcc
	v_lshlrev_b32_e32 v166, 2, v144
	v_mul_f32_e32 v144, v125, v125
	v_fmac_f32_e32 v144, v124, v124
	v_add_f32_e32 v144, v144, v164
	v_mul_f32_e32 v164, v121, v121
	v_mul_f32_e32 v165, v123, v123
	v_fmac_f32_e32 v164, v120, v120
	v_fmac_f32_e32 v165, v122, v122
	v_add_f32_e32 v164, v164, v165
	v_add_f32_e32 v144, v144, v164
	v_mov_b32_e32 v254, v144
	v_mov_b32_e32 v255, v144
	s_nop 1
	v_permlane16_swap_b32_e32 v254, v255
	v_add_f32_e32 v164, v254, v255
	v_xor_b32_e32 v165, 32, v182
	v_cmp_lt_i32_e32 vcc, v165, v163
	s_lshl_b32 s11, s10, 8
	v_readlane_b32 s18, v253, 7
	v_cndmask_b32_e32 v163, v182, v165, vcc
	v_lshlrev_b32_e32 v167, 2, v163
	s_waitcnt lgkmcnt(0)
	v_mov_b32_e32 v144, v164
	v_mov_b32_e32 v254, v144
	v_mov_b32_e32 v255, v144
	s_nop 1
	v_permlane32_swap_b32_e32 v254, v255
	v_add_f32_e32 v163, v254, v255
	v_add_u32_e32 v164, s11, v170
	v_ashrrev_i32_e32 v165, 31, v164
	v_readlane_b32 s19, v253, 8
	v_readlane_b32 s22, v253, 11
	v_readlane_b32 s23, v253, 12
	v_readlane_b32 s24, v253, 13
	v_readlane_b32 s25, v253, 14
	v_readlane_b32 s26, v253, 15
	v_readlane_b32 s27, v253, 16
	v_readlane_b32 s28, v253, 17
	v_readlane_b32 s29, v253, 18
	v_readlane_b32 s30, v253, 19
	v_readlane_b32 s31, v253, 20
	s_and_saveexec_b64 s[8:9], s[4:5]
	s_xor_b64 s[8:9], exec, s[8:9]
	s_or_saveexec_b64 s[8:9], s[8:9]
	s_lshl_b32 s34, s54, 3
	s_ashr_i32 s35, s34, 31
	s_movk_i32 s18, 0x90
	s_xor_b64 exec, exec, s[8:9]
	s_cbranch_execz .LBB0_400
	v_mov_b64_e32 v[168:169], s[82:83]
	v_mad_i64_i32 v[168:169], s[38:39], v164, s18, v[168:169]
	v_lshl_add_u64 v[168:169], s[34:35], 2, v[168:169]
	s_lshl_b32 s80, s15, 2
	s_waitcnt lgkmcnt(0)
	v_mov_b32_e32 v144, v163
	v_lshl_add_u64 v[168:169], v[168:169], 0, s[80:81]
	global_store_dword v[168:169], v144, off

.LBB0_406:
	v_lshlrev_b32_e32 v144, 1, v152
	v_lshl_add_u64 v[124:125], v[124:125], 0, v[144:145]
	global_store_dwordx4 v[124:125], v[120:123], off
	s_nop 1
	v_mul_f32_e32 v121, v117, v117
	v_mul_f32_e32 v122, v119, v119
	v_fmac_f32_e32 v121, v116, v116
	v_fmac_f32_e32 v122, v118, v118
	v_add_f32_e32 v121, v121, v122
	v_mul_f32_e32 v122, v113, v113
	v_mul_f32_e32 v123, v115, v115
	v_fmac_f32_e32 v122, v112, v112
	v_fmac_f32_e32 v123, v114, v114
	v_add_f32_e32 v122, v122, v123
	v_add_f32_e32 v121, v121, v122
	v_mov_b32_e32 v254, v121
	v_mov_b32_e32 v255, v121
	s_nop 1
	v_permlane16_swap_b32_e32 v254, v255
	v_add_f32_e32 v122, v254, v255
	v_add_u32_e32 v120, s11, v172
	s_waitcnt lgkmcnt(0)
	v_mov_b32_e32 v254, v122
	v_mov_b32_e32 v255, v122
	s_nop 1
	v_permlane32_swap_b32_e32 v254, v255
	v_add_f32_e32 v123, v254, v255
	v_ashrrev_i32_e32 v121, 31, v120
	s_and_saveexec_b64 s[2:3], s[4:5]
	s_xor_b64 s[2:3], exec, s[2:3]
	s_andn2_saveexec_b64 s[2:3], s[2:3]
	s_cbranch_execz .LBB0_410
	s_waitcnt lgkmcnt(0)
	v_mov_b32_e32 v124, v123
	v_mov_b64_e32 v[122:123], s[82:83]
	v_mad_i64_i32 v[122:123], s[38:39], v120, s18, v[122:123]
	v_lshl_add_u64 v[122:123], s[34:35], 2, v[122:123]
	s_lshl_b32 s38, s15, 2
	s_mov_b32 s39, s81
	v_lshl_add_u64 v[122:123], v[122:123], 0, s[38:39]
	global_store_dword v[122:123], v124, off

.LBB0_416:
	v_lshl_add_u64 v[116:117], v[116:117], 0, v[144:145]
	global_store_dwordx4 v[116:117], v[112:115], off
	s_nop 1
	v_mul_f32_e32 v113, v109, v109
	v_mul_f32_e32 v114, v111, v111
	v_fmac_f32_e32 v113, v108, v108
	v_fmac_f32_e32 v114, v110, v110
	v_add_f32_e32 v113, v113, v114
	v_mul_f32_e32 v114, v105, v105
	v_mul_f32_e32 v115, v107, v107
	v_fmac_f32_e32 v114, v104, v104
	v_fmac_f32_e32 v115, v106, v106
	v_add_f32_e32 v114, v114, v115
	v_add_f32_e32 v113, v113, v114
	v_mov_b32_e32 v254, v113
	v_mov_b32_e32 v255, v113
	s_nop 1
	v_permlane16_swap_b32_e32 v254, v255
	v_add_f32_e32 v114, v254, v255
	v_add_u32_e32 v112, s11, v173
	s_waitcnt lgkmcnt(0)
	v_mov_b32_e32 v254, v114
	v_mov_b32_e32 v255, v114
	s_nop 1
	v_permlane32_swap_b32_e32 v254, v255
	v_add_f32_e32 v115, v254, v255
	v_ashrrev_i32_e32 v113, 31, v112
	s_and_saveexec_b64 s[2:3], s[4:5]
	s_xor_b64 s[2:3], exec, s[2:3]
	s_andn2_saveexec_b64 s[2:3], s[2:3]
	s_cbranch_execz .LBB0_420
	s_waitcnt lgkmcnt(0)
	v_mov_b32_e32 v116, v115
	v_mov_b64_e32 v[114:115], s[82:83]
	v_mad_i64_i32 v[114:115], s[38:39], v112, s18, v[114:115]
	v_lshl_add_u64 v[114:115], s[34:35], 2, v[114:115]
	s_lshl_b32 s38, s15, 2
	s_mov_b32 s39, s81
	v_lshl_add_u64 v[114:115], v[114:115], 0, s[38:39]
	global_store_dword v[114:115], v116, off

.LBB0_426:
	v_lshl_add_u64 v[108:109], v[108:109], 0, v[144:145]
	global_store_dwordx4 v[108:109], v[104:107], off
	s_nop 1
	v_mul_f32_e32 v105, v101, v101
	v_mul_f32_e32 v106, v103, v103
	v_fmac_f32_e32 v105, v100, v100
	v_fmac_f32_e32 v106, v102, v102
	v_add_f32_e32 v105, v105, v106
	v_mul_f32_e32 v106, v97, v97
	v_mul_f32_e32 v107, v99, v99
	v_fmac_f32_e32 v106, v96, v96
	v_fmac_f32_e32 v107, v98, v98
	v_add_f32_e32 v106, v106, v107
	v_add_f32_e32 v105, v105, v106
	v_mov_b32_e32 v254, v105
	v_mov_b32_e32 v255, v105
	s_nop 1
	v_permlane16_swap_b32_e32 v254, v255
	v_add_f32_e32 v106, v254, v255
	v_add_u32_e32 v104, s11, v174
	s_waitcnt lgkmcnt(0)
	v_mov_b32_e32 v254, v106
	v_mov_b32_e32 v255, v106
	s_nop 1
	v_permlane32_swap_b32_e32 v254, v255
	v_add_f32_e32 v107, v254, v255
	v_ashrrev_i32_e32 v105, 31, v104
	s_and_saveexec_b64 s[2:3], s[4:5]
	s_xor_b64 s[2:3], exec, s[2:3]
	s_andn2_saveexec_b64 s[2:3], s[2:3]
	s_cbranch_execz .LBB0_430
	s_waitcnt lgkmcnt(0)
	v_mov_b32_e32 v108, v107
	v_mov_b64_e32 v[106:107], s[82:83]
	v_mad_i64_i32 v[106:107], s[38:39], v104, s18, v[106:107]
	v_lshl_add_u64 v[106:107], s[34:35], 2, v[106:107]
	s_lshl_b32 s38, s15, 2
	s_mov_b32 s39, s81
	v_lshl_add_u64 v[106:107], v[106:107], 0, s[38:39]
	global_store_dword v[106:107], v108, off

.LBB0_436:
	v_lshl_add_u64 v[100:101], v[100:101], 0, v[144:145]
	global_store_dwordx4 v[100:101], v[96:99], off
	s_nop 1
	v_mul_f32_e32 v97, v93, v93
	v_mul_f32_e32 v98, v95, v95
	v_fmac_f32_e32 v97, v92, v92
	v_fmac_f32_e32 v98, v94, v94
	v_add_f32_e32 v97, v97, v98
	v_mul_f32_e32 v98, v89, v89
	v_mul_f32_e32 v99, v91, v91
	v_fmac_f32_e32 v98, v88, v88
	v_fmac_f32_e32 v99, v90, v90
	v_add_f32_e32 v98, v98, v99
	v_add_f32_e32 v97, v97, v98
	v_mov_b32_e32 v254, v97
	v_mov_b32_e32 v255, v97
	s_nop 1
	v_permlane16_swap_b32_e32 v254, v255
	v_add_f32_e32 v98, v254, v255
	v_add_u32_e32 v96, s11, v175
	s_waitcnt lgkmcnt(0)
	v_mov_b32_e32 v254, v98
	v_mov_b32_e32 v255, v98
	s_nop 1
	v_permlane32_swap_b32_e32 v254, v255
	v_add_f32_e32 v99, v254, v255
	v_ashrrev_i32_e32 v97, 31, v96
	s_and_saveexec_b64 s[2:3], s[4:5]
	s_xor_b64 s[2:3], exec, s[2:3]
	s_andn2_saveexec_b64 s[2:3], s[2:3]
	s_cbranch_execz .LBB0_440
	s_waitcnt lgkmcnt(0)
	v_mov_b32_e32 v100, v99
	v_mov_b64_e32 v[98:99], s[82:83]
	v_mad_i64_i32 v[98:99], s[38:39], v96, s18, v[98:99]
	v_lshl_add_u64 v[98:99], s[34:35], 2, v[98:99]
	s_lshl_b32 s38, s15, 2
	s_mov_b32 s39, s81
	v_lshl_add_u64 v[98:99], v[98:99], 0, s[38:39]
	global_store_dword v[98:99], v100, off

.LBB0_446:
	v_lshl_add_u64 v[92:93], v[92:93], 0, v[144:145]
	global_store_dwordx4 v[92:93], v[88:91], off
	s_nop 1
	v_mul_f32_e32 v89, v85, v85
	v_mul_f32_e32 v90, v87, v87
	v_fmac_f32_e32 v89, v84, v84
	v_fmac_f32_e32 v90, v86, v86
	v_add_f32_e32 v89, v89, v90
	v_mul_f32_e32 v90, v81, v81
	v_mul_f32_e32 v91, v83, v83
	v_fmac_f32_e32 v90, v80, v80
	v_fmac_f32_e32 v91, v82, v82
	v_add_f32_e32 v90, v90, v91
	v_add_f32_e32 v89, v89, v90
	v_mov_b32_e32 v254, v89
	v_mov_b32_e32 v255, v89
	s_nop 1
	v_permlane16_swap_b32_e32 v254, v255
	v_add_f32_e32 v90, v254, v255
	v_add_u32_e32 v88, s11, v176
	s_waitcnt lgkmcnt(0)
	v_mov_b32_e32 v254, v90
	v_mov_b32_e32 v255, v90
	s_nop 1
	v_permlane32_swap_b32_e32 v254, v255
	v_add_f32_e32 v91, v254, v255
	v_ashrrev_i32_e32 v89, 31, v88
	s_and_saveexec_b64 s[2:3], s[4:5]
	s_xor_b64 s[2:3], exec, s[2:3]
	s_andn2_saveexec_b64 s[2:3], s[2:3]
	s_cbranch_execz .LBB0_450
	s_waitcnt lgkmcnt(0)
	v_mov_b32_e32 v92, v91
	v_mov_b64_e32 v[90:91], s[82:83]
	v_mad_i64_i32 v[90:91], s[38:39], v88, s18, v[90:91]
	v_lshl_add_u64 v[90:91], s[34:35], 2, v[90:91]
	s_lshl_b32 s38, s15, 2
	s_mov_b32 s39, s81
	v_lshl_add_u64 v[90:91], v[90:91], 0, s[38:39]
	global_store_dword v[90:91], v92, off

.LBB0_456:
	v_lshl_add_u64 v[84:85], v[84:85], 0, v[144:145]
	global_store_dwordx4 v[84:85], v[80:83], off
	s_nop 1
	v_mul_f32_e32 v81, v77, v77
	v_mul_f32_e32 v82, v79, v79
	v_fmac_f32_e32 v81, v76, v76
	v_fmac_f32_e32 v82, v78, v78
	v_add_f32_e32 v81, v81, v82
	v_mul_f32_e32 v82, v73, v73
	v_mul_f32_e32 v83, v75, v75
	v_fmac_f32_e32 v82, v72, v72
	v_fmac_f32_e32 v83, v74, v74
	v_add_f32_e32 v82, v82, v83
	v_add_f32_e32 v81, v81, v82
	v_mov_b32_e32 v254, v81
	v_mov_b32_e32 v255, v81
	s_nop 1
	v_permlane16_swap_b32_e32 v254, v255
	v_add_f32_e32 v82, v254, v255
	v_add_u32_e32 v80, s11, v177
	s_waitcnt lgkmcnt(0)
	v_mov_b32_e32 v254, v82
	v_mov_b32_e32 v255, v82
	s_nop 1
	v_permlane32_swap_b32_e32 v254, v255
	v_add_f32_e32 v83, v254, v255
	v_ashrrev_i32_e32 v81, 31, v80
	s_and_saveexec_b64 s[2:3], s[4:5]
	s_xor_b64 s[2:3], exec, s[2:3]
	s_andn2_saveexec_b64 s[2:3], s[2:3]
	s_cbranch_execz .LBB0_460
	s_waitcnt lgkmcnt(0)
	v_mov_b32_e32 v84, v83
	v_mov_b64_e32 v[82:83], s[82:83]
	v_mad_i64_i32 v[82:83], s[38:39], v80, s18, v[82:83]
	v_lshl_add_u64 v[82:83], s[34:35], 2, v[82:83]
	s_lshl_b32 s38, s15, 2
	s_mov_b32 s39, s81
	v_lshl_add_u64 v[82:83], v[82:83], 0, s[38:39]
	global_store_dword v[82:83], v84, off

.LBB0_466:
	v_lshl_add_u64 v[76:77], v[76:77], 0, v[144:145]
	global_store_dwordx4 v[76:77], v[72:75], off
	s_nop 1
	v_mul_f32_e32 v73, v69, v69
	v_mul_f32_e32 v74, v71, v71
	v_fmac_f32_e32 v73, v68, v68
	v_fmac_f32_e32 v74, v70, v70
	v_add_f32_e32 v73, v73, v74
	v_mul_f32_e32 v74, v65, v65
	v_mul_f32_e32 v75, v67, v67
	v_fmac_f32_e32 v74, v64, v64
	v_fmac_f32_e32 v75, v66, v66
	v_add_f32_e32 v74, v74, v75
	v_add_f32_e32 v73, v73, v74
	v_mov_b32_e32 v254, v73
	v_mov_b32_e32 v255, v73
	s_nop 1
	v_permlane16_swap_b32_e32 v254, v255
	v_add_f32_e32 v74, v254, v255
	v_add_u32_e32 v72, s11, v178
	s_waitcnt lgkmcnt(0)
	v_mov_b32_e32 v254, v74
	v_mov_b32_e32 v255, v74
	s_nop 1
	v_permlane32_swap_b32_e32 v254, v255
	v_add_f32_e32 v75, v254, v255
	v_ashrrev_i32_e32 v73, 31, v72
	s_and_saveexec_b64 s[2:3], s[4:5]
	s_xor_b64 s[2:3], exec, s[2:3]
	s_andn2_saveexec_b64 s[2:3], s[2:3]
	s_cbranch_execz .LBB0_470
	s_waitcnt lgkmcnt(0)
	v_mov_b32_e32 v76, v75
	v_mov_b64_e32 v[74:75], s[82:83]
	v_mad_i64_i32 v[74:75], s[38:39], v72, s18, v[74:75]
	v_lshl_add_u64 v[74:75], s[34:35], 2, v[74:75]
	s_lshl_b32 s34, s15, 2
	s_mov_b32 s35, s81
	v_lshl_add_u64 v[74:75], v[74:75], 0, s[34:35]
	global_store_dword v[74:75], v76, off

.LBB0_551:
	s_cmp_lt_i32 s54, 1
	s_cselect_b64 s[86:87], -1, 0
	s_lshl_b32 s56, s11, 7
	s_mov_b32 s57, s81
	v_readlane_b32 s16, v253, 5
	s_lshl_b64 s[2:3], s[56:57], 2
	v_readlane_b32 s24, v253, 13
	v_readlane_b32 s25, v253, 14
	s_add_u32 s2, s24, s2
	s_addc_u32 s3, s25, s3
	s_add_u32 s8, s2, 0xfffffa00
	s_addc_u32 s9, s3, -1
	s_ashr_i32 s57, s56, 31
	v_readlane_b32 s20, v253, 9
	s_lshl_b64 s[2:3], s[56:57], 2
	v_readlane_b32 s21, v253, 10
	s_add_u32 s34, s20, s2
	s_addc_u32 s35, s21, s3
	v_readlane_b32 s17, v253, 6
	s_cmp_gt_i32 s54, 0
	s_cselect_b64 s[16:17], -1, 0
	s_and_b64 s[2:3], s[16:17], exec
	s_cselect_b32 s3, s9, s35
	s_cselect_b32 s2, s8, s34
	global_load_dwordx4 v[64:67], v162, s[2:3] offset:16
	s_waitcnt lgkmcnt(0)
	global_load_dwordx4 v[68:71], v162, s[2:3]
	v_and_b32_e32 v73, 64, v182
	v_xor_b32_e32 v72, 16, v182
	v_add_u32_e32 v73, 64, v73
	v_cmp_lt_i32_e32 vcc, v72, v73
	v_mul_f32_e32 v75, v63, v63
	v_fmac_f32_e32 v75, v62, v62
	v_cndmask_b32_e32 v72, v182, v72, vcc
	v_lshlrev_b32_e32 v74, 2, v72
	v_mul_f32_e32 v72, v61, v61
	v_fmac_f32_e32 v72, v60, v60
	v_add_f32_e32 v72, v72, v75
	v_mul_f32_e32 v75, v57, v57
	v_mul_f32_e32 v76, v59, v59
	v_fmac_f32_e32 v75, v56, v56
	v_fmac_f32_e32 v76, v58, v58
	v_add_f32_e32 v75, v75, v76
	v_add_f32_e32 v72, v72, v75
	v_mov_b32_e32 v254, v72
	v_mov_b32_e32 v255, v72
	s_nop 1
	v_permlane16_swap_b32_e32 v254, v255
	v_add_f32_e32 v76, v254, v255
	v_xor_b32_e32 v75, 32, v182
	v_cmp_lt_i32_e32 vcc, v75, v73
	s_lshl_b32 s37, s10, 8
	v_readlane_b32 s18, v253, 7
	v_cndmask_b32_e32 v73, v182, v75, vcc
	v_lshlrev_b32_e32 v75, 2, v73
	s_waitcnt lgkmcnt(0)
	v_mov_b32_e32 v254, v76
	v_mov_b32_e32 v255, v76
	s_nop 1
	v_permlane32_swap_b32_e32 v254, v255
	v_add_f32_e32 v77, v254, v255
	v_add_u32_e32 v72, s37, v170
	v_ashrrev_i32_e32 v73, 31, v72
	v_readlane_b32 s19, v253, 8
	v_readlane_b32 s22, v253, 11
	v_readlane_b32 s23, v253, 12
	v_readlane_b32 s26, v253, 15
	v_readlane_b32 s27, v253, 16
	v_readlane_b32 s28, v253, 17
	v_readlane_b32 s29, v253, 18
	v_readlane_b32 s30, v253, 19
	v_readlane_b32 s31, v253, 20
	s_and_saveexec_b64 s[2:3], s[4:5]
	s_xor_b64 s[2:3], exec, s[2:3]
	s_or_saveexec_b64 s[2:3], s[2:3]
	s_lshl_b32 s10, s11, 2
	s_ashr_i32 s11, s10, 31
	s_movk_i32 s18, 0x90
	s_xor_b64 exec, exec, s[2:3]
	s_cbranch_execz .LBB0_555
	s_waitcnt lgkmcnt(0)
	v_mov_b32_e32 v78, v77
	v_mov_b64_e32 v[76:77], s[82:83]
	v_mad_i64_i32 v[76:77], s[8:9], v72, s18, v[76:77]
	v_lshl_add_u64 v[76:77], s[10:11], 2, v[76:77]
	s_lshl_b32 s80, s15, 2
	v_lshl_add_u64 v[76:77], v[76:77], 0, s[80:81]
	global_store_dword v[76:77], v78, off

.LBB0_561:
	v_lshlrev_b32_e32 v144, 1, v152
	v_lshl_add_u64 v[60:61], v[60:61], 0, v[144:145]
	global_store_dwordx4 v[60:61], v[56:59], off
	s_nop 1
	v_mul_f32_e32 v57, v53, v53
	v_mul_f32_e32 v58, v55, v55
	v_fmac_f32_e32 v57, v52, v52
	v_fmac_f32_e32 v58, v54, v54
	v_add_f32_e32 v57, v57, v58
	v_mul_f32_e32 v58, v49, v49
	v_mul_f32_e32 v59, v51, v51
	v_fmac_f32_e32 v58, v48, v48
	v_fmac_f32_e32 v59, v50, v50
	v_add_f32_e32 v58, v58, v59
	v_add_f32_e32 v57, v57, v58
	v_mov_b32_e32 v254, v57
	v_mov_b32_e32 v255, v57
	s_nop 1
	v_permlane16_swap_b32_e32 v254, v255
	v_add_f32_e32 v58, v254, v255
	v_add_u32_e32 v56, s37, v172
	s_waitcnt lgkmcnt(0)
	v_mov_b32_e32 v254, v58
	v_mov_b32_e32 v255, v58
	s_nop 1
	v_permlane32_swap_b32_e32 v254, v255
	v_add_f32_e32 v59, v254, v255
	v_ashrrev_i32_e32 v57, 31, v56
	s_and_saveexec_b64 s[2:3], s[4:5]
	s_xor_b64 s[2:3], exec, s[2:3]
	s_andn2_saveexec_b64 s[2:3], s[2:3]
	s_cbranch_execz .LBB0_565
	s_waitcnt lgkmcnt(0)
	v_mov_b32_e32 v60, v59
	v_mov_b64_e32 v[58:59], s[82:83]
	v_mad_i64_i32 v[58:59], s[38:39], v56, s18, v[58:59]
	v_lshl_add_u64 v[58:59], s[10:11], 2, v[58:59]
	s_lshl_b32 s38, s15, 2
	s_mov_b32 s39, s81
	v_lshl_add_u64 v[58:59], v[58:59], 0, s[38:39]
	global_store_dword v[58:59], v60, off

.LBB0_571:
	v_lshl_add_u64 v[52:53], v[52:53], 0, v[144:145]
	global_store_dwordx4 v[52:53], v[48:51], off
	s_nop 1
	v_mul_f32_e32 v49, v45, v45
	v_mul_f32_e32 v50, v47, v47
	v_fmac_f32_e32 v49, v44, v44
	v_fmac_f32_e32 v50, v46, v46
	v_add_f32_e32 v49, v49, v50
	v_mul_f32_e32 v50, v41, v41
	v_mul_f32_e32 v51, v43, v43
	v_fmac_f32_e32 v50, v40, v40
	v_fmac_f32_e32 v51, v42, v42
	v_add_f32_e32 v50, v50, v51
	v_add_f32_e32 v49, v49, v50
	v_mov_b32_e32 v254, v49
	v_mov_b32_e32 v255, v49
	s_nop 1
	v_permlane16_swap_b32_e32 v254, v255
	v_add_f32_e32 v50, v254, v255
	v_add_u32_e32 v48, s37, v173
	s_waitcnt lgkmcnt(0)
	v_mov_b32_e32 v254, v50
	v_mov_b32_e32 v255, v50
	s_nop 1
	v_permlane32_swap_b32_e32 v254, v255
	v_add_f32_e32 v51, v254, v255
	v_ashrrev_i32_e32 v49, 31, v48
	s_and_saveexec_b64 s[2:3], s[4:5]
	s_xor_b64 s[2:3], exec, s[2:3]
	s_andn2_saveexec_b64 s[2:3], s[2:3]
	s_cbranch_execz .LBB0_575
	s_waitcnt lgkmcnt(0)
	v_mov_b32_e32 v52, v51
	v_mov_b64_e32 v[50:51], s[82:83]
	v_mad_i64_i32 v[50:51], s[38:39], v48, s18, v[50:51]
	v_lshl_add_u64 v[50:51], s[10:11], 2, v[50:51]
	s_lshl_b32 s38, s15, 2
	s_mov_b32 s39, s81
	v_lshl_add_u64 v[50:51], v[50:51], 0, s[38:39]
	global_store_dword v[50:51], v52, off

.LBB0_581:
	v_lshl_add_u64 v[44:45], v[44:45], 0, v[144:145]
	global_store_dwordx4 v[44:45], v[40:43], off
	s_nop 1
	v_mul_f32_e32 v41, v37, v37
	v_mul_f32_e32 v42, v39, v39
	v_fmac_f32_e32 v41, v36, v36
	v_fmac_f32_e32 v42, v38, v38
	v_add_f32_e32 v41, v41, v42
	v_mul_f32_e32 v42, v33, v33
	v_mul_f32_e32 v43, v35, v35
	v_fmac_f32_e32 v42, v32, v32
	v_fmac_f32_e32 v43, v34, v34
	v_add_f32_e32 v42, v42, v43
	v_add_f32_e32 v41, v41, v42
	v_mov_b32_e32 v254, v41
	v_mov_b32_e32 v255, v41
	s_nop 1
	v_permlane16_swap_b32_e32 v254, v255
	v_add_f32_e32 v42, v254, v255
	v_add_u32_e32 v40, s37, v174
	s_waitcnt lgkmcnt(0)
	v_mov_b32_e32 v254, v42
	v_mov_b32_e32 v255, v42
	s_nop 1
	v_permlane32_swap_b32_e32 v254, v255
	v_add_f32_e32 v43, v254, v255
	v_ashrrev_i32_e32 v41, 31, v40
	s_and_saveexec_b64 s[2:3], s[4:5]
	s_xor_b64 s[2:3], exec, s[2:3]
	s_andn2_saveexec_b64 s[2:3], s[2:3]
	s_cbranch_execz .LBB0_585
	s_waitcnt lgkmcnt(0)
	v_mov_b32_e32 v44, v43
	v_mov_b64_e32 v[42:43], s[82:83]
	v_mad_i64_i32 v[42:43], s[38:39], v40, s18, v[42:43]
	v_lshl_add_u64 v[42:43], s[10:11], 2, v[42:43]
	s_lshl_b32 s38, s15, 2
	s_mov_b32 s39, s81
	v_lshl_add_u64 v[42:43], v[42:43], 0, s[38:39]
	global_store_dword v[42:43], v44, off

.LBB0_591:
	v_lshl_add_u64 v[36:37], v[36:37], 0, v[144:145]
	global_store_dwordx4 v[36:37], v[32:35], off
	s_nop 1
	v_mul_f32_e32 v33, v29, v29
	v_mul_f32_e32 v34, v31, v31
	v_fmac_f32_e32 v33, v28, v28
	v_fmac_f32_e32 v34, v30, v30
	v_add_f32_e32 v33, v33, v34
	v_mul_f32_e32 v34, v25, v25
	v_mul_f32_e32 v35, v27, v27
	v_fmac_f32_e32 v34, v24, v24
	v_fmac_f32_e32 v35, v26, v26
	v_add_f32_e32 v34, v34, v35
	v_add_f32_e32 v33, v33, v34
	v_mov_b32_e32 v254, v33
	v_mov_b32_e32 v255, v33
	s_nop 1
	v_permlane16_swap_b32_e32 v254, v255
	v_add_f32_e32 v34, v254, v255
	v_add_u32_e32 v32, s37, v175
	s_waitcnt lgkmcnt(0)
	v_mov_b32_e32 v254, v34
	v_mov_b32_e32 v255, v34
	s_nop 1
	v_permlane32_swap_b32_e32 v254, v255
	v_add_f32_e32 v35, v254, v255
	v_ashrrev_i32_e32 v33, 31, v32
	s_and_saveexec_b64 s[2:3], s[4:5]
	s_xor_b64 s[2:3], exec, s[2:3]
	s_andn2_saveexec_b64 s[2:3], s[2:3]
	s_cbranch_execz .LBB0_595
	s_waitcnt lgkmcnt(0)
	v_mov_b32_e32 v36, v35
	v_mov_b64_e32 v[34:35], s[82:83]
	v_mad_i64_i32 v[34:35], s[38:39], v32, s18, v[34:35]
	v_lshl_add_u64 v[34:35], s[10:11], 2, v[34:35]
	s_lshl_b32 s38, s15, 2
	s_mov_b32 s39, s81
	v_lshl_add_u64 v[34:35], v[34:35], 0, s[38:39]
	global_store_dword v[34:35], v36, off

.LBB0_601:
	v_lshl_add_u64 v[28:29], v[28:29], 0, v[144:145]
	global_store_dwordx4 v[28:29], v[24:27], off
	s_nop 1
	v_mul_f32_e32 v25, v21, v21
	v_mul_f32_e32 v26, v23, v23
	v_fmac_f32_e32 v25, v20, v20
	v_fmac_f32_e32 v26, v22, v22
	v_add_f32_e32 v25, v25, v26
	v_mul_f32_e32 v26, v17, v17
	v_mul_f32_e32 v27, v19, v19
	v_fmac_f32_e32 v26, v16, v16
	v_fmac_f32_e32 v27, v18, v18
	v_add_f32_e32 v26, v26, v27
	v_add_f32_e32 v25, v25, v26
	v_mov_b32_e32 v254, v25
	v_mov_b32_e32 v255, v25
	s_nop 1
	v_permlane16_swap_b32_e32 v254, v255
	v_add_f32_e32 v26, v254, v255
	v_add_u32_e32 v24, s37, v176
	s_waitcnt lgkmcnt(0)
	v_mov_b32_e32 v254, v26
	v_mov_b32_e32 v255, v26
	s_nop 1
	v_permlane32_swap_b32_e32 v254, v255
	v_add_f32_e32 v27, v254, v255
	v_ashrrev_i32_e32 v25, 31, v24
	s_and_saveexec_b64 s[2:3], s[4:5]
	s_xor_b64 s[2:3], exec, s[2:3]
	s_andn2_saveexec_b64 s[2:3], s[2:3]
	s_cbranch_execz .LBB0_605
	s_waitcnt lgkmcnt(0)
	v_mov_b32_e32 v28, v27
	v_mov_b64_e32 v[26:27], s[82:83]
	v_mad_i64_i32 v[26:27], s[38:39], v24, s18, v[26:27]
	v_lshl_add_u64 v[26:27], s[10:11], 2, v[26:27]
	s_lshl_b32 s38, s15, 2
	s_mov_b32 s39, s81
	v_lshl_add_u64 v[26:27], v[26:27], 0, s[38:39]
	global_store_dword v[26:27], v28, off

.LBB0_611:
	v_lshl_add_u64 v[20:21], v[20:21], 0, v[144:145]
	global_store_dwordx4 v[20:21], v[16:19], off
	s_nop 1
	v_mul_f32_e32 v17, v13, v13
	v_mul_f32_e32 v18, v15, v15
	v_fmac_f32_e32 v17, v12, v12
	v_fmac_f32_e32 v18, v14, v14
	v_add_f32_e32 v17, v17, v18
	v_mul_f32_e32 v18, v9, v9
	v_mul_f32_e32 v19, v11, v11
	v_fmac_f32_e32 v18, v8, v8
	v_fmac_f32_e32 v19, v10, v10
	v_add_f32_e32 v18, v18, v19
	v_add_f32_e32 v17, v17, v18
	v_mov_b32_e32 v254, v17
	v_mov_b32_e32 v255, v17
	s_nop 1
	v_permlane16_swap_b32_e32 v254, v255
	v_add_f32_e32 v18, v254, v255
	v_add_u32_e32 v16, s37, v177
	s_waitcnt lgkmcnt(0)
	v_mov_b32_e32 v254, v18
	v_mov_b32_e32 v255, v18
	s_nop 1
	v_permlane32_swap_b32_e32 v254, v255
	v_add_f32_e32 v19, v254, v255
	v_ashrrev_i32_e32 v17, 31, v16
	s_and_saveexec_b64 s[2:3], s[4:5]
	s_xor_b64 s[2:3], exec, s[2:3]
	s_andn2_saveexec_b64 s[2:3], s[2:3]
	s_cbranch_execz .LBB0_615
	s_waitcnt lgkmcnt(0)
	v_mov_b32_e32 v20, v19
	v_mov_b64_e32 v[18:19], s[82:83]
	v_mad_i64_i32 v[18:19], s[38:39], v16, s18, v[18:19]
	v_lshl_add_u64 v[18:19], s[10:11], 2, v[18:19]
	s_lshl_b32 s38, s15, 2
	s_mov_b32 s39, s81
	v_lshl_add_u64 v[18:19], v[18:19], 0, s[38:39]
	global_store_dword v[18:19], v20, off

.LBB0_621:
	v_lshl_add_u64 v[12:13], v[12:13], 0, v[144:145]
	global_store_dwordx4 v[12:13], v[8:11], off
	s_nop 1
	v_mul_f32_e32 v9, v5, v5
	v_mul_f32_e32 v10, v7, v7
	v_fmac_f32_e32 v9, v4, v4
	v_fmac_f32_e32 v10, v6, v6
	v_add_f32_e32 v9, v9, v10
	v_mul_f32_e32 v10, v1, v1
	v_mul_f32_e32 v11, v3, v3
	v_fmac_f32_e32 v10, v0, v0
	v_fmac_f32_e32 v11, v2, v2
	v_add_f32_e32 v10, v10, v11
	v_add_f32_e32 v9, v9, v10
	v_mov_b32_e32 v254, v9
	v_mov_b32_e32 v255, v9
	s_nop 1
	v_permlane16_swap_b32_e32 v254, v255
	v_add_f32_e32 v10, v254, v255
	v_add_u32_e32 v8, s37, v178
	s_waitcnt lgkmcnt(0)
	v_mov_b32_e32 v254, v10
	v_mov_b32_e32 v255, v10
	s_nop 1
	v_permlane32_swap_b32_e32 v254, v255
	v_add_f32_e32 v11, v254, v255
	v_ashrrev_i32_e32 v9, 31, v8
	s_and_saveexec_b64 s[2:3], s[4:5]
	s_xor_b64 s[2:3], exec, s[2:3]
	s_andn2_saveexec_b64 s[2:3], s[2:3]
	s_cbranch_execz .LBB0_625
	s_waitcnt lgkmcnt(0)
	v_mov_b32_e32 v12, v11
	v_mov_b64_e32 v[10:11], s[82:83]
	v_mad_i64_i32 v[10:11], s[38:39], v8, s18, v[10:11]
	v_lshl_add_u64 v[10:11], s[10:11], 2, v[10:11]
	s_lshl_b32 s10, s15, 2
	s_mov_b32 s11, s81
	v_lshl_add_u64 v[10:11], v[10:11], 0, s[10:11]
	global_store_dword v[10:11], v12, off

	.amdhsa_kernel _Z6mk_fwd4Args
		.amdhsa_group_segment_fixed_size 0
		.amdhsa_private_segment_fixed_size 0
		.amdhsa_kernarg_size 488
		.amdhsa_user_sgpr_count 2
		.amdhsa_user_sgpr_dispatch_ptr 0
		.amdhsa_user_sgpr_queue_ptr 0
		.amdhsa_user_sgpr_kernarg_segment_ptr 1
		.amdhsa_user_sgpr_dispatch_id 0
		.amdhsa_user_sgpr_kernarg_preload_length 0
		.amdhsa_user_sgpr_kernarg_preload_offset 0
		.amdhsa_user_sgpr_private_segment_size 0
		.amdhsa_uses_dynamic_stack 0
		.amdhsa_enable_private_segment 0
		.amdhsa_system_sgpr_workgroup_id_x 1
		.amdhsa_system_sgpr_workgroup_id_y 0
		.amdhsa_system_sgpr_workgroup_id_z 0
		.amdhsa_system_sgpr_workgroup_info 0
		.amdhsa_system_vgpr_workitem_id 2
		.amdhsa_next_free_vgpr 256
		.amdhsa_next_free_sgpr 98
		.amdhsa_accum_offset 256
		.amdhsa_reserve_vcc 1
		.amdhsa_float_round_mode_32 0
		.amdhsa_float_round_mode_16_64 0
		.amdhsa_float_denorm_mode_32 3
		.amdhsa_float_denorm_mode_16_64 3
		.amdhsa_dx10_clamp 1
		.amdhsa_ieee_mode 1
		.amdhsa_fp16_overflow 0
		.amdhsa_tg_split 0
		.amdhsa_exception_fp_ieee_invalid_op 0
		.amdhsa_exception_fp_denorm_src 0
		.amdhsa_exception_fp_ieee_div_zero 0
		.amdhsa_exception_fp_ieee_overflow 0
		.amdhsa_exception_fp_ieee_underflow 0
		.amdhsa_exception_fp_ieee_inexact 0
		.amdhsa_exception_int_div_zero 0
	.end_amdhsa_kernel

.Lfunc_end0:
	.size	_Z6mk_fwd4Args, .Lfunc_end0-_Z6mk_fwd4Args
	.set _Z6mk_fwd4Args.num_vgpr, 256
	.set _Z6mk_fwd4Args.num_agpr, 0
	.set _Z6mk_fwd4Args.numbered_sgpr, 98
	.set _Z6mk_fwd4Args.num_named_barrier, 0
	.set _Z6mk_fwd4Args.private_seg_size, 0
	.set _Z6mk_fwd4Args.uses_vcc, 1
	.set _Z6mk_fwd4Args.uses_flat_scratch, 0
	.set _Z6mk_fwd4Args.has_dyn_sized_stack, 0
	.set _Z6mk_fwd4Args.has_recursion, 0
	.set _Z6mk_fwd4Args.has_indirect_call, 0

amdhsa.kernels:
  - .agpr_count:     0
    .args:
      - .offset:         0
        .size:           232
        .value_kind:     by_value
      - .offset:         232
        .size:           4
        .value_kind:     hidden_block_count_x
      - .offset:         236
        .size:           4
        .value_kind:     hidden_block_count_y
      - .offset:         240
        .size:           4
        .value_kind:     hidden_block_count_z
      - .offset:         244
        .size:           2
        .value_kind:     hidden_group_size_x
      - .offset:         246
        .size:           2
        .value_kind:     hidden_group_size_y
      - .offset:         248
        .size:           2
        .value_kind:     hidden_group_size_z
      - .offset:         250
        .size:           2
        .value_kind:     hidden_remainder_x
      - .offset:         252
        .size:           2
        .value_kind:     hidden_remainder_y
      - .offset:         254
        .size:           2
        .value_kind:     hidden_remainder_z
      - .offset:         272
        .size:           8
        .value_kind:     hidden_global_offset_x
      - .offset:         280
        .size:           8
        .value_kind:     hidden_global_offset_y
      - .offset:         288
        .size:           8
        .value_kind:     hidden_global_offset_z
      - .offset:         296
        .size:           2
        .value_kind:     hidden_grid_dims
      - .offset:         320
        .size:           8
        .value_kind:     hidden_multigrid_sync_arg
      - .offset:         352
        .size:           4
        .value_kind:     hidden_dynamic_lds_size
    .group_segment_fixed_size: 0
    .kernarg_segment_align: 8
    .kernarg_segment_size: 488
    .language:       OpenCL C
    .language_version:
      - 2
      - 0
    .max_flat_workgroup_size: 512
    .name:           _Z6mk_fwd4Args
    .private_segment_fixed_size: 0
    .sgpr_count:     104
    .sgpr_spill_count: 84
    .symbol:         _Z6mk_fwd4Args.kd
    .uniform_work_group_size: 1
    .uses_dynamic_stack: false
    .vgpr_count:     256
    .vgpr_spill_count: 0
    .wavefront_size: 64
